# v27 + attention LDS-DMA piece rebalancing: the odd K piece issued by wave 7 instead of wave 0 (max loads per wave per step 5->4 diff, 7->6 MLA)
# speedup vs baseline: 1.0089x; 1.0089x over previous
; template <int DQK>
; __device__ __forceinline__ void attn_pass4(LAS unsigned char* lds, const bf16* Qp, int qpitch, const bf16* Kp, int kpitch, const bf16* Vp, int vpitch, int q0, f32x16 (&o)[4], float (&rl)[16]) {
;     ...
;     constexpr int KS = G::KP / 16, KD = DQK / 8, KJ = (KS + 7) / 8, VS = VP / 16, VD = 16, VJ = (VS + 7) / 8;
;     unsigned koff[KJ], voff[VJ];
; #pragma unroll
;     for (int j = 0; j < KJ; ++j) { const int sidx = (j * 8 + wid) * 64 + lane, row = (sidx / KS) & 63, c = sidx % KS; koff[j] = (unsigned)(row * kpitch + (c < KD ? c : KD - 1) * 8) * 2u; }
; #pragma unroll
;     for (int j = 0; j < VJ; ++j) { const int sidx = (j * 8 + wid) * 64 + lane, row = (sidx / VS) & 63, c = sidx % VS; voff[j] = (unsigned)(row * vpitch + (c < VD ? c : VD - 1) * 8) * 2u; }
.LBB0_611:
	v_add_u32_e32 v36, 0x200, v35
	v_and_b32_e32 v98, 63, v35
	v_or_b32_e32 v98, 0x200, v98
	v_mul_hi_i32 v37, v98, s85
	v_lshrrev_b32_e32 v38, 31, v37
	v_ashrrev_i32_e32 v37, 1, v37
	v_add_u32_e32 v37, v37, v38
	v_lshl_add_u32 v38, v37, 3, v37
	v_sub_u32_e32 v38, v98, v38
	v_lshlrev_b32_e32 v37, 11, v37
	s_add_i32 s2, s3, 8
	v_and_b32_e32 v37, 0x1f800, v37
	v_min_i32_e32 v38, 7, v38
	s_cmp_gt_i32 s3, 6
	s_cselect_b64 s[10:11], -1, 0
	s_cmp_lt_i32 s3, 7
	v_lshl_add_u32 v176, v38, 4, v37
	s_cbranch_scc1 .LBB0_613
	v_mov_b32_e32 v177, v33
	s_movk_i32 s8, 0x2000
	v_lshl_add_u64 v[38:39], s[52:53], 0, v[176:177]
	s_mov_b32 m0, s8
	s_nop 0
	global_load_lds_dwordx4 v[38:39], off

; template <int DQK>
; __device__ __forceinline__ void attn_pass4(LAS unsigned char* lds, const bf16* Qp, int qpitch, const bf16* Kp, int kpitch, const bf16* Vp, int vpitch, int q0, f32x16 (&o)[4], float (&rl)[16]) {
;     ...
;     constexpr int KS = G::KP / 16, KD = DQK / 8, KJ = (KS + 7) / 8, VS = VP / 16, VD = 16, VJ = (VS + 7) / 8;
;     unsigned koff[KJ], voff[VJ];
; #pragma unroll
;     for (int j = 0; j < KJ; ++j) { const int sidx = (j * 8 + wid) * 64 + lane, row = (sidx / KS) & 63, c = sidx % KS; koff[j] = (unsigned)(row * kpitch + (c < KD ? c : KD - 1) * 8) * 2u; }
; #pragma unroll
;     for (int j = 0; j < VJ; ++j) { const int sidx = (j * 8 + wid) * 64 + lane, row = (sidx / VS) & 63, c = sidx % VS; voff[j] = (unsigned)(row * vpitch + (c < VD ? c : VD - 1) * 8) * 2u; }
;     ...
; #pragma unroll
;     for (int db = 0; db < 4; ++db)
; #pragma unroll
;         for (int r = 0; r < 16; ++r) o[db][r] = 0.f;
;     float mhat = 0.f, l = 0.f;
;     f32x16 negm;
; #pragma unroll
;     for (int r = 0; r < 16; ++r) negm[r] = 0.f;
;     u32x4 pw[4];
.LBB0_619:
	s_andn2_b32 s5, s5, 63
	s_lshl_b32 s5, s5, 2
	s_add_i32 s8, s30, 0x100
	s_add_i32 s81, s5, 0
	s_waitcnt vmcnt(0) lgkmcnt(0)
	s_barrier
	v_and_b32_e32 v167, 63, v32
	s_add_i32 s81, s81, 0x13800
	s_lshr_b32 s31, s8, 6
	v_mul_u32_u24_e32 v35, 0x90, v34
	v_lshlrev_b32_e32 v36, 1, v32
	v_lshlrev_b32_e32 v37, 3, v32
	s_cmp_lt_i32 s3, 8
	s_mov_b64 s[70:71], -1
	v_cmp_gt_u32_e64 s[8:9], 32, v167
	v_add3_u32 v188, 0, v35, v168
	v_lshlrev_b32_e32 v190, 2, v180
	v_lshl_add_u32 v169, v34, 2, s81
	v_lshrrev_b32_e32 v192, 2, v32
	v_and_b32_e32 v184, 32, v36
	v_and_b32_e32 v186, 24, v37
	s_cbranch_scc0 .LBB0_642
	v_and_or_b32 v32, v192, 3, v190
	v_mad_u32_u24 v32, v32, s82, 0
	v_mov_b32_e32 v46, v33
	v_mov_b32_e32 v47, v33
	v_add3_u32 v194, v32, v184, v186
	v_mov_b32_e32 v32, v33
	v_mov_b32_e32 v34, v33
	v_mov_b32_e32 v35, v33
	v_mov_b32_e32 v36, v33
	v_mov_b32_e32 v37, v33
	v_mov_b32_e32 v38, v33
	v_mov_b32_e32 v39, v33
	v_mov_b32_e32 v40, v33
	v_mov_b32_e32 v41, v33
	v_mov_b32_e32 v42, v33
	v_mov_b32_e32 v43, v33
	v_mov_b32_e32 v44, v33
	v_mov_b32_e32 v45, v33
	v_mov_b64_e32 v[96:97], v[46:47]
	v_mov_b64_e32 v[80:81], v[46:47]
	v_mov_b64_e32 v[64:65], v[46:47]
	s_lshl_b32 s5, s3, 10
	v_mov_b32_e32 v196, 0
	v_mov_b64_e32 v[94:95], v[44:45]
	v_mov_b64_e32 v[92:93], v[42:43]
	v_mov_b64_e32 v[90:91], v[40:41]
	v_mov_b64_e32 v[88:89], v[38:39]
	v_mov_b64_e32 v[86:87], v[36:37]
	v_mov_b64_e32 v[84:85], v[34:35]
	v_mov_b64_e32 v[82:83], v[32:33]
	v_mov_b64_e32 v[78:79], v[44:45]
	v_mov_b64_e32 v[76:77], v[42:43]
	v_mov_b64_e32 v[74:75], v[40:41]
	v_mov_b64_e32 v[72:73], v[38:39]
	v_mov_b64_e32 v[70:71], v[36:37]
	v_mov_b64_e32 v[68:69], v[34:35]
	v_mov_b64_e32 v[66:67], v[32:33]
	v_mov_b64_e32 v[62:63], v[44:45]
	v_mov_b64_e32 v[60:61], v[42:43]
	v_mov_b64_e32 v[58:59], v[40:41]
	v_mov_b64_e32 v[56:57], v[38:39]
	v_mov_b64_e32 v[54:55], v[36:37]
	v_mov_b64_e32 v[52:53], v[34:35]
	v_mov_b64_e32 v[50:51], v[32:33]
	v_mov_b64_e32 v[48:49], v[46:47]
	s_add_i32 s26, s5, 0x4800
	s_or_b32 s27, s76, 31
	v_mov_b32_e32 v171, v33
	v_mov_b32_e32 v177, v33
	s_movk_i32 s80, 0x2000
	v_mov_b32_e32 v173, v33
	v_mov_b32_e32 v175, v33
	v_mov_b32_e32 v179, v33
	s_mov_b32 s24, 0
	s_mov_b32 s18, 63
	s_mov_b64 s[70:71], s[60:61]
	v_mov_b64_e32 v[46:47], v[44:45]
	v_mov_b64_e32 v[44:45], v[42:43]
	v_mov_b64_e32 v[42:43], v[40:41]
	v_mov_b64_e32 v[40:41], v[38:39]
	v_mov_b64_e32 v[38:39], v[36:37]
	v_mov_b64_e32 v[36:37], v[34:35]
	v_mov_b64_e32 v[34:35], v[32:33]
	v_mov_b32_e32 v182, 0
	s_mov_b32 s72, 0
	v_mov_b32_e32 v98, 0
	v_mov_b32_e32 v99, v196
	v_mov_b32_e32 v100, v196
	v_mov_b32_e32 v101, v196
	v_mov_b32_e32 v102, v196
	v_mov_b32_e32 v103, v196
	v_mov_b32_e32 v104, v196
	v_mov_b32_e32 v105, v196
	v_mov_b32_e32 v106, v196
	v_mov_b32_e32 v107, v196
	v_mov_b32_e32 v108, v196
	v_mov_b32_e32 v109, v196
	v_mov_b32_e32 v110, v196
	v_mov_b32_e32 v111, v196
	v_mov_b32_e32 v112, v196
	v_mov_b32_e32 v113, v196

; template <int DQK>
; __device__ __forceinline__ void attn_pass4(LAS unsigned char* lds, const bf16* Qp, int qpitch, const bf16* Kp, int kpitch, const bf16* Vp, int vpitch, int q0, f32x16 (&o)[4], float (&rl)[16]) {
;     ...
;     constexpr int KS = G::KP / 16, KD = DQK / 8, KJ = (KS + 7) / 8, VS = VP / 16, VD = 16, VJ = (VS + 7) / 8;
;     unsigned koff[KJ], voff[VJ];
; #pragma unroll
;     for (int j = 0; j < KJ; ++j) { const int sidx = (j * 8 + wid) * 64 + lane, row = (sidx / KS) & 63, c = sidx % KS; koff[j] = (unsigned)(row * kpitch + (c < KD ? c : KD - 1) * 8) * 2u; }
; #pragma unroll
;     for (int j = 0; j < VJ; ++j) { const int sidx = (j * 8 + wid) * 64 + lane, row = (sidx / VS) & 63, c = sidx % VS; voff[j] = (unsigned)(row * vpitch + (c < VD ? c : VD - 1) * 8) * 2u; }
.LBB0_811:
	v_add_u32_e32 v36, 0x200, v35
	v_and_b32_e32 v98, 63, v35
	v_or_b32_e32 v98, 0x200, v98
	v_mul_hi_i32 v37, v98, s85
	v_lshrrev_b32_e32 v38, 31, v37
	v_ashrrev_i32_e32 v37, 1, v37
	v_add_u32_e32 v37, v37, v38
	v_lshl_add_u32 v38, v37, 3, v37
	v_sub_u32_e32 v38, v98, v38
	v_lshlrev_b32_e32 v37, 11, v37
	s_add_i32 s2, s80, 8
	v_and_b32_e32 v37, 0x1f800, v37
	v_min_i32_e32 v38, 7, v38
	s_cmp_gt_i32 s80, 6
	s_cselect_b64 s[10:11], -1, 0
	s_cmp_lt_i32 s80, 7
	v_lshl_add_u32 v176, v38, 4, v37
	s_cbranch_scc1 .LBB0_813
	v_mov_b32_e32 v177, v33
	s_movk_i32 s5, 0x2000
	v_lshl_add_u64 v[38:39], s[56:57], 0, v[176:177]
	s_mov_b32 m0, s5
	s_nop 0
	global_load_lds_dwordx4 v[38:39], off

; template <int DQK>
; __device__ __forceinline__ void attn_pass4(LAS unsigned char* lds, const bf16* Qp, int qpitch, const bf16* Kp, int kpitch, const bf16* Vp, int vpitch, int q0, f32x16 (&o)[4], float (&rl)[16]) {
;     ...
;     constexpr int KS = G::KP / 16, KD = DQK / 8, KJ = (KS + 7) / 8, VS = VP / 16, VD = 16, VJ = (VS + 7) / 8;
;     unsigned koff[KJ], voff[VJ];
; #pragma unroll
;     for (int j = 0; j < KJ; ++j) { const int sidx = (j * 8 + wid) * 64 + lane, row = (sidx / KS) & 63, c = sidx % KS; koff[j] = (unsigned)(row * kpitch + (c < KD ? c : KD - 1) * 8) * 2u; }
; #pragma unroll
;     for (int j = 0; j < VJ; ++j) { const int sidx = (j * 8 + wid) * 64 + lane, row = (sidx / VS) & 63, c = sidx % VS; voff[j] = (unsigned)(row * vpitch + (c < VD ? c : VD - 1) * 8) * 2u; }
;     ...
; #pragma unroll
;     for (int db = 0; db < 4; ++db)
; #pragma unroll
;         for (int r = 0; r < 16; ++r) o[db][r] = 0.f;
;     float mhat = 0.f, l = 0.f;
;     f32x16 negm;
; #pragma unroll
;     for (int r = 0; r < 16; ++r) negm[r] = 0.f;
;     u32x4 pw[4];
.LBB0_819:
	s_andn2_b32 s3, s3, 63
	s_lshl_b32 s3, s3, 2
	s_add_i32 s81, s3, 0
	s_waitcnt vmcnt(0) lgkmcnt(0)
	s_barrier
	v_and_b32_e32 v167, 63, v32
	s_add_i32 s81, s81, 0x13800
	v_mul_u32_u24_e32 v35, 0x90, v34
	v_lshlrev_b32_e32 v36, 1, v32
	v_lshlrev_b32_e32 v37, 3, v32
	s_cmp_lt_i32 s80, 8
	s_mov_b64 s[70:71], -1
	v_cmp_gt_u32_e64 s[8:9], 32, v167
	v_add3_u32 v188, 0, v35, v168
	v_lshlrev_b32_e32 v190, 2, v180
	v_lshl_add_u32 v169, v34, 2, s81
	v_lshrrev_b32_e32 v192, 2, v32
	v_and_b32_e32 v184, 32, v36
	v_and_b32_e32 v186, 24, v37
	s_cbranch_scc0 .LBB0_842
	v_and_or_b32 v32, v192, 3, v190
	v_mad_u32_u24 v32, v32, s82, 0
	v_mov_b32_e32 v46, v33
	v_mov_b32_e32 v47, v33
	v_add3_u32 v194, v32, v184, v186
	v_mov_b32_e32 v32, v33
	v_mov_b32_e32 v34, v33
	v_mov_b32_e32 v35, v33
	v_mov_b32_e32 v36, v33
	v_mov_b32_e32 v37, v33
	v_mov_b32_e32 v38, v33
	v_mov_b32_e32 v39, v33
	v_mov_b32_e32 v40, v33
	v_mov_b32_e32 v41, v33
	v_mov_b32_e32 v42, v33
	v_mov_b32_e32 v43, v33
	v_mov_b32_e32 v44, v33
	v_mov_b32_e32 v45, v33
	v_mov_b64_e32 v[96:97], v[46:47]
	v_mov_b64_e32 v[80:81], v[46:47]
	v_mov_b64_e32 v[64:65], v[46:47]
	s_lshl_b32 s3, s80, 10
	v_mov_b32_e32 v196, 0
	v_mov_b64_e32 v[94:95], v[44:45]
	v_mov_b64_e32 v[92:93], v[42:43]
	v_mov_b64_e32 v[90:91], v[40:41]
	v_mov_b64_e32 v[88:89], v[38:39]
	v_mov_b64_e32 v[86:87], v[36:37]
	v_mov_b64_e32 v[84:85], v[34:35]
	v_mov_b64_e32 v[82:83], v[32:33]
	v_mov_b64_e32 v[78:79], v[44:45]
	v_mov_b64_e32 v[76:77], v[42:43]
	v_mov_b64_e32 v[74:75], v[40:41]
	v_mov_b64_e32 v[72:73], v[38:39]
	v_mov_b64_e32 v[70:71], v[36:37]
	v_mov_b64_e32 v[68:69], v[34:35]
	v_mov_b64_e32 v[66:67], v[32:33]
	v_mov_b64_e32 v[62:63], v[44:45]
	v_mov_b64_e32 v[60:61], v[42:43]
	v_mov_b64_e32 v[58:59], v[40:41]
	v_mov_b64_e32 v[56:57], v[38:39]
	v_mov_b64_e32 v[54:55], v[36:37]
	v_mov_b64_e32 v[52:53], v[34:35]
	v_mov_b64_e32 v[50:51], v[32:33]
	v_mov_b64_e32 v[48:49], v[46:47]
	s_add_i32 s5, s3, 0x4800
	s_or_b32 s26, s76, 31
	v_mov_b32_e32 v171, v33
	v_mov_b32_e32 v177, v33
	s_movk_i32 s27, 0x2000
	v_mov_b32_e32 v173, v33
	v_mov_b32_e32 v175, v33
	v_mov_b32_e32 v179, v33
	s_mov_b32 s35, 0
	s_mov_b32 s18, 63
	s_mov_b64 s[70:71], s[62:63]
	v_mov_b64_e32 v[46:47], v[44:45]
	v_mov_b64_e32 v[44:45], v[42:43]
	v_mov_b64_e32 v[42:43], v[40:41]
	v_mov_b64_e32 v[40:41], v[38:39]
	v_mov_b64_e32 v[38:39], v[36:37]
	v_mov_b64_e32 v[36:37], v[34:35]
	v_mov_b64_e32 v[34:35], v[32:33]
	v_mov_b32_e32 v182, 0
	s_mov_b32 s72, 0
	v_mov_b32_e32 v98, 0
	v_mov_b32_e32 v99, v196
	v_mov_b32_e32 v100, v196
	v_mov_b32_e32 v101, v196
	v_mov_b32_e32 v102, v196
	v_mov_b32_e32 v103, v196
	v_mov_b32_e32 v104, v196
	v_mov_b32_e32 v105, v196
	v_mov_b32_e32 v106, v196
	v_mov_b32_e32 v107, v196
	v_mov_b32_e32 v108, v196
	v_mov_b32_e32 v109, v196
	v_mov_b32_e32 v110, v196
	v_mov_b32_e32 v111, v196
	v_mov_b32_e32 v112, v196
	v_mov_b32_e32 v113, v196

; template <int DQK>
; __device__ __forceinline__ void attn_pass4(LAS unsigned char* lds, const bf16* Qp, int qpitch, const bf16* Kp, int kpitch, const bf16* Vp, int vpitch, int q0, f32x16 (&o)[4], float (&rl)[16]) {
;     ...
;     constexpr int KS = G::KP / 16, KD = DQK / 8, KJ = (KS + 7) / 8, VS = VP / 16, VD = 16, VJ = (VS + 7) / 8;
;     unsigned koff[KJ], voff[VJ];
; #pragma unroll
;     for (int j = 0; j < KJ; ++j) { const int sidx = (j * 8 + wid) * 64 + lane, row = (sidx / KS) & 63, c = sidx % KS; koff[j] = (unsigned)(row * kpitch + (c < KD ? c : KD - 1) * 8) * 2u; }
; #pragma unroll
;     for (int j = 0; j < VJ; ++j) { const int sidx = (j * 8 + wid) * 64 + lane, row = (sidx / VS) & 63, c = sidx % VS; voff[j] = (unsigned)(row * vpitch + (c < VD ? c : VD - 1) * 8) * 2u; }
.LBB0_2141:
	v_and_b32_e32 v6, 63, v3
	v_or_b32_e32 v6, 0x600, v6
	v_mul_hi_i32 v7, v6, s26
	v_lshrrev_b32_e32 v8, 31, v7
	v_ashrrev_i32_e32 v7, 3, v7
	v_add_u32_e32 v7, v7, v8
	v_and_b32_e32 v8, 63, v7
	v_mul_lo_u32 v7, v7, 25
	v_sub_u32_e32 v6, v6, v7
	s_add_i32 s58, s67, 24
	v_min_i32_e32 v6, 23, v6
	v_mul_u32_u24_e32 v7, 0xc00, v8
	s_cmp_gt_i32 s67, 6
	s_cselect_b64 s[12:13], -1, 0
	s_cmp_lt_i32 s67, 7
	v_lshl_add_u32 v190, v6, 4, v7
	s_cbranch_scc1 .LBB0_2143
	v_mov_b32_e32 v191, v1
	s_movk_i32 s3, 0x6000
	v_lshl_add_u64 v[6:7], s[34:35], 0, v[190:191]
	s_mov_b32 m0, s3
	s_nop 0
	global_load_lds_dwordx4 v[6:7], off

; template <int DQK>
; __device__ __forceinline__ void attn_pass4(LAS unsigned char* lds, const bf16* Qp, int qpitch, const bf16* Kp, int kpitch, const bf16* Vp, int vpitch, int q0, f32x16 (&o)[4], float (&rl)[16]) {
;     ...
;     constexpr int KS = G::KP / 16, KD = DQK / 8, KJ = (KS + 7) / 8, VS = VP / 16, VD = 16, VJ = (VS + 7) / 8;
;     unsigned koff[KJ], voff[VJ];
; #pragma unroll
;     for (int j = 0; j < KJ; ++j) { const int sidx = (j * 8 + wid) * 64 + lane, row = (sidx / KS) & 63, c = sidx % KS; koff[j] = (unsigned)(row * kpitch + (c < KD ? c : KD - 1) * 8) * 2u; }
; #pragma unroll
;     for (int j = 0; j < VJ; ++j) { const int sidx = (j * 8 + wid) * 64 + lane, row = (sidx / VS) & 63, c = sidx % VS; voff[j] = (unsigned)(row * vpitch + (c < VD ? c : VD - 1) * 8) * 2u; }
;     ...
; #pragma unroll
;     for (int db = 0; db < 4; ++db)
; #pragma unroll
;         for (int r = 0; r < 16; ++r) o[db][r] = 0.f;
;     float mhat = 0.f, l = 0.f;
;     f32x16 negm;
; #pragma unroll
;     for (int r = 0; r < 16; ++r) negm[r] = 0.f;
;     u32x4 pw[4];
.LBB0_2149:
	s_andn2_b32 s2, s2, 63
	s_lshl_b32 s2, s2, 2
	s_add_i32 s10, s66, 0x100
	s_add_i32 s3, s2, 0
	s_waitcnt vmcnt(0) lgkmcnt(0)
	s_barrier
	v_and_b32_e32 v179, 63, v0
	s_add_i32 s3, s3, 0x1b800
	s_lshr_b32 s69, s10, 6
	v_mul_u32_u24_e32 v3, 0x190, v2
	v_lshlrev_b32_e32 v4, 1, v0
	v_lshlrev_b32_e32 v5, 3, v0
	s_cmp_lt_i32 s67, 8
	s_mov_b64 s[56:57], -1
	v_cmp_gt_u32_e64 s[10:11], 32, v179
	v_add3_u32 v200, 0, v3, v178
	v_lshlrev_b32_e32 v201, 2, v195
	v_lshl_add_u32 v196, v2, 2, s3
	v_lshrrev_b32_e32 v202, 2, v0
	v_and_b32_e32 v198, 32, v4
	v_and_b32_e32 v199, 24, v5
	s_cbranch_scc0 .LBB0_2172
	v_and_or_b32 v0, v202, 3, v201
	v_mad_u32_u24 v0, v0, s30, 0
	v_mov_b32_e32 v14, v1
	v_mov_b32_e32 v15, v1
	s_lshl_b32 s2, s67, 10
	v_add3_u32 v203, v0, v198, v199
	v_mov_b32_e32 v0, v1
	v_mov_b32_e32 v2, v1
	v_mov_b32_e32 v3, v1
	v_mov_b32_e32 v4, v1
	v_mov_b32_e32 v5, v1
	v_mov_b32_e32 v6, v1
	v_mov_b32_e32 v7, v1
	v_mov_b32_e32 v8, v1
	v_mov_b32_e32 v9, v1
	v_mov_b32_e32 v10, v1
	v_mov_b32_e32 v11, v1
	v_mov_b32_e32 v12, v1
	v_mov_b32_e32 v13, v1
	v_mov_b32_e32 v204, 0
	v_mov_b64_e32 v[30:31], v[14:15]
	v_mov_b64_e32 v[46:47], v[14:15]
	v_mov_b64_e32 v[62:63], v[14:15]
	v_mov_b64_e32 v[78:79], v[14:15]
	s_add_i32 s24, s2, 0xc800
	s_or_b32 s25, s68, 31
	v_mov_b32_e32 v181, v1
	v_mov_b32_e32 v183, v1
	s_lshl_b32 s72, s70, 10
	v_mov_b32_e32 v185, v1
	s_lshl_b32 s73, s71, 10
	v_mov_b32_e32 v191, v1
	s_movk_i32 s74, 0x6000
	v_mov_b32_e32 v187, v1
	v_mov_b32_e32 v189, v1
	v_mov_b32_e32 v193, v1
	s_mov_b32 s78, 0
	s_mov_b32 s75, 63
	s_mov_b64 s[56:57], s[42:43]
	s_mov_b64 s[58:59], s[40:41]
	v_mov_b64_e32 v[28:29], v[12:13]
	v_mov_b64_e32 v[26:27], v[10:11]
	v_mov_b64_e32 v[24:25], v[8:9]
	v_mov_b64_e32 v[22:23], v[6:7]
	v_mov_b64_e32 v[20:21], v[4:5]
	v_mov_b64_e32 v[18:19], v[2:3]
	v_mov_b64_e32 v[16:17], v[0:1]
	v_mov_b64_e32 v[44:45], v[12:13]
	v_mov_b64_e32 v[42:43], v[10:11]
	v_mov_b64_e32 v[40:41], v[8:9]
	v_mov_b64_e32 v[38:39], v[6:7]
	v_mov_b64_e32 v[36:37], v[4:5]
	v_mov_b64_e32 v[34:35], v[2:3]
	v_mov_b64_e32 v[32:33], v[0:1]
	v_mov_b64_e32 v[60:61], v[12:13]
	v_mov_b64_e32 v[58:59], v[10:11]
	v_mov_b64_e32 v[56:57], v[8:9]
	v_mov_b64_e32 v[54:55], v[6:7]
	v_mov_b64_e32 v[52:53], v[4:5]
	v_mov_b64_e32 v[50:51], v[2:3]
	v_mov_b64_e32 v[48:49], v[0:1]
	v_mov_b64_e32 v[76:77], v[12:13]
	v_mov_b64_e32 v[74:75], v[10:11]
	v_mov_b64_e32 v[72:73], v[8:9]
	v_mov_b64_e32 v[70:71], v[6:7]
	v_mov_b64_e32 v[68:69], v[4:5]
	v_mov_b64_e32 v[66:67], v[2:3]
	v_mov_b64_e32 v[64:65], v[0:1]
	v_mov_b32_e32 v2, 0
	s_mov_b32 s60, 0
	v_mov_b32_e32 v80, 0
	v_mov_b32_e32 v81, v204
	v_mov_b32_e32 v82, v204
	v_mov_b32_e32 v83, v204
	v_mov_b32_e32 v84, v204
	v_mov_b32_e32 v85, v204
	v_mov_b32_e32 v86, v204
	v_mov_b32_e32 v87, v204
	v_mov_b32_e32 v88, v204
	v_mov_b32_e32 v89, v204
	v_mov_b32_e32 v90, v204
	v_mov_b32_e32 v91, v204
	v_mov_b32_e32 v92, v204
	v_mov_b32_e32 v93, v204
	v_mov_b32_e32 v94, v204
	v_mov_b32_e32 v95, v204
